# cache policy: nt on the bf16 residual-stream stores (ROW1, ROW2) and the final f32 output stores
# speedup vs baseline: 1.0317x; 1.0008x over previous
; __device__ __forceinline__ f32x4 bf4(u32x2 q) { return (f32x4){__uint_as_float(q.x << 16), __uint_as_float(q.x & 0xffff0000u), __uint_as_float(q.y << 16), __uint_as_float(q.y & 0xffff0000u)}; }
; __device__ __forceinline__ void ln_stats(const f32x4 (&v)[4], float& mean, float& rstd) {
;     float s = 0.f;
; #pragma unroll
;     for (int j = 0; j < 4; ++j) s += (v[j].x + v[j].y) + (v[j].z + v[j].w);
;     mean = wsum(s) * (1.f / D);
; __device__ __forceinline__ void deepnorm_r(f32x4 (&x)[4], const f32x4 (&y)[4], const f32x4 (&g1)[4], const f32x4 (&lg)[4], const f32x4 (&lb)[4]) {
; #pragma unroll
;     for (int j = 0; j < 4; ++j) x[j] = ALPHA * x[j] + g1[j] * y[j];
;     float mean, rstd; ln_stats(x, mean, rstd);
; __device__ __forceinline__ void phase_row1(const Frame& F, int l) {
;     ...
;         for (int i = 0; i < 8; ++i) {
;             const int row = chunk * 64 + w * 8 + i, b = row >> 11;
;             const float* modp = MOD + ((size_t)l * 8 + b) * 6144;
;             if (i + 1 < 8) { if (l == 0) load_row(F.in[0] + (size_t)(row + 1) * D, lane, nx); else load_row_bf16(XB + (size_t)(row + 1) * D, lane, nx);
; #pragma unroll
;                 for (int j = 0; j < 4; ++j) ny[j] = *(const u32x2*)((const bf16*)(F.ws + WS_MIX) + (size_t)(row + 1) * D + 256 * j + 4 * lane); }
;             f32x4 x[4], y[4];
; #pragma unroll
;             for (int j = 0; j < 4; ++j) { x[j] = cx[j]; y[j] = bf4(cy[j]); }
;             deepnorm_r(x, y, g1, vlg, vlb);
.LBB0_2147:
	v_lshlrev_b32_e32 v164, 16, v152
	v_and_b32_e32 v165, 0xffff0000, v152
	v_lshlrev_b32_e32 v152, 16, v153
	v_and_b32_e32 v153, 0xffff0000, v153
	v_lshlrev_b32_e32 v168, 16, v148
	v_and_b32_e32 v169, 0xffff0000, v148
	v_lshlrev_b32_e32 v148, 16, v149
	v_and_b32_e32 v149, 0xffff0000, v149
	v_lshlrev_b32_e32 v166, 16, v150
	v_and_b32_e32 v167, 0xffff0000, v150
	v_lshlrev_b32_e32 v150, 16, v151
	v_and_b32_e32 v151, 0xffff0000, v151
	v_lshlrev_b32_e32 v170, 16, v146
	v_and_b32_e32 v171, 0xffff0000, v146
	v_lshlrev_b32_e32 v146, 16, v147
	v_and_b32_e32 v147, 0xffff0000, v147
	v_pk_mul_f32 v[164:165], v[94:95], v[164:165]
	v_pk_mul_f32 v[152:153], v[96:97], v[152:153]
	v_pk_mul_f32 v[148:149], v[88:89], v[148:149]
	v_pk_fma_f32 v[80:81], v[80:81], s[16:17], v[152:153] op_sel_hi:[1,0,1]
	v_pk_fma_f32 v[78:79], v[78:79], s[16:17], v[164:165] op_sel_hi:[1,0,1]
	v_pk_mul_f32 v[152:153], v[90:91], v[166:167]
	v_pk_mul_f32 v[150:151], v[92:93], v[150:151]
	v_pk_fma_f32 v[72:73], v[72:73], s[16:17], v[148:149] op_sel_hi:[1,0,1]
	v_pk_mul_f32 v[148:149], v[82:83], v[170:171]
	v_pk_mul_f32 v[146:147], v[84:85], v[146:147]
	v_pk_fma_f32 v[76:77], v[76:77], s[16:17], v[150:151] op_sel_hi:[1,0,1]
	v_pk_fma_f32 v[74:75], v[74:75], s[16:17], v[152:153] op_sel_hi:[1,0,1]
	v_pk_mul_f32 v[150:151], v[86:87], v[168:169]
	v_pk_fma_f32 v[68:69], v[68:69], s[16:17], v[146:147] op_sel_hi:[1,0,1]
	v_pk_fma_f32 v[66:67], v[66:67], s[16:17], v[148:149] op_sel_hi:[1,0,1]
	v_pk_mov_b32 v[146:147], v[78:79], v[80:81] op_sel:[1,0]
	v_mov_b32_e32 v148, v78
	v_mov_b32_e32 v149, v81
	v_pk_fma_f32 v[70:71], v[70:71], s[16:17], v[150:151] op_sel_hi:[1,0,1]
	v_pk_add_f32 v[146:147], v[146:147], v[148:149]
	v_pk_mov_b32 v[148:149], v[74:75], v[76:77] op_sel:[1,0]
	v_mov_b32_e32 v150, v74
	v_mov_b32_e32 v151, v77
	v_pk_add_f32 v[148:149], v[148:149], v[150:151]
	v_add_f32_e32 v146, v146, v147
	v_pk_add_f32 v[148:149], v[148:149], v[148:149] op_sel:[0,1] op_sel_hi:[1,0]
	v_add_f32_e32 v146, 0, v146
	v_add_f32_e32 v150, v70, v71
	v_add_f32_e32 v152, v72, v73
	v_mov_b32_e32 v147, v66
	v_mov_b32_e32 v149, v67
	v_mov_b32_e32 v151, v68
	v_mov_b32_e32 v153, v69
	v_pk_add_f32 v[146:147], v[146:147], v[148:149]
	v_pk_add_f32 v[148:149], v[150:151], v[152:153]
	s_ashr_i32 s27, s26, 31
	v_pk_add_f32 v[146:147], v[146:147], v[148:149]
	s_lshl_b64 s[30:31], s[26:27], 11
	v_add_f32_e32 v146, v146, v147
	ds_bpermute_b32 v147, v135, v146
	s_mov_b32 s7, 0x1e3ce508
	s_waitcnt lgkmcnt(0)
	v_add_f32_e32 v146, v146, v147
	ds_bpermute_b32 v147, v159, v146
	s_waitcnt lgkmcnt(0)
	v_add_f32_e32 v146, v146, v147
	ds_bpermute_b32 v147, v160, v146
	s_waitcnt lgkmcnt(0)
	v_add_f32_e32 v146, v146, v147
	ds_bpermute_b32 v147, v161, v146
	s_waitcnt lgkmcnt(0)
	v_add_f32_e32 v146, v146, v147
	ds_bpermute_b32 v147, v162, v146
	s_waitcnt lgkmcnt(0)
	v_add_f32_e32 v146, v146, v147
	ds_bpermute_b32 v147, v163, v146
	s_waitcnt lgkmcnt(0)
	v_add_f32_e32 v164, v146, v147
	v_fmamk_f32 v79, v164, 0xba800000, v79
	v_fmac_f32_e32 v78, 0xba800000, v164
	v_fmamk_f32 v81, v164, 0xba800000, v81
	v_fmac_f32_e32 v80, 0xba800000, v164
	v_pk_mul_f32 v[146:147], v[80:81], v[80:81]
	v_pk_mul_f32 v[148:149], v[78:79], v[78:79]
	v_fmamk_f32 v75, v164, 0xba800000, v75
	v_pk_mov_b32 v[150:151], v[148:149], v[146:147] op_sel:[1,0]
	v_mov_b32_e32 v149, v147
	v_pk_add_f32 v[146:147], v[150:151], v[148:149]
	v_fmac_f32_e32 v74, 0xba800000, v164
	v_fmamk_f32 v77, v164, 0xba800000, v77
	v_fmac_f32_e32 v76, 0xba800000, v164
	v_pk_add_f32 v[146:147], v[146:147], v[146:147] op_sel_hi:[0,1]
	v_pk_mul_f32 v[148:149], v[76:77], v[76:77]
	v_pk_mul_f32 v[150:151], v[74:75], v[74:75]
	v_fmac_f32_e32 v70, 0xba800000, v164
	v_pk_mov_b32 v[152:153], v[150:151], v[148:149] op_sel:[1,0]
	v_mov_b32_e32 v151, v149
	v_fmamk_f32 v71, v164, 0xba800000, v71
	v_fmac_f32_e32 v72, 0xba800000, v164
	v_mul_f32_e32 v146, v70, v70
	v_pk_add_f32 v[148:149], v[152:153], v[150:151]
	v_fmamk_f32 v73, v164, 0xba800000, v73
	v_pk_fma_f32 v[150:151], v[70:71], v[70:71], v[146:147] op_sel_hi:[1,1,0]
	v_mul_f32_e32 v146, v72, v72
	v_pk_add_f32 v[148:149], v[148:149], v[148:149] op_sel_hi:[0,1]
	v_pk_fma_f32 v[152:153], v[72:73], v[72:73], v[146:147] op_sel_hi:[1,1,0]
	v_fmamk_f32 v69, v164, 0xba800000, v69
	v_fmac_f32_e32 v68, 0xba800000, v164
	v_fmamk_f32 v67, v164, 0xba800000, v67
	v_fmac_f32_e32 v66, 0xba800000, v164
	v_mul_f32_e32 v150, v66, v66
	v_mul_f32_e32 v152, v67, v67
	v_mul_f32_e32 v146, v68, v68
	v_mul_f32_e32 v148, v69, v69
	v_pk_add_f32 v[150:151], v[150:151], v[152:153]
	v_pk_add_f32 v[146:147], v[146:147], v[148:149]
	s_nop 0
	v_pk_add_f32 v[146:147], v[150:151], v[146:147]
	s_nop 0
	v_add_f32_e32 v146, v146, v147
	ds_bpermute_b32 v147, v135, v146
	s_waitcnt lgkmcnt(0)
	v_add_f32_e32 v146, v146, v147
	ds_bpermute_b32 v147, v159, v146
	s_waitcnt lgkmcnt(0)
	v_add_f32_e32 v146, v146, v147
	ds_bpermute_b32 v147, v160, v146
	s_waitcnt lgkmcnt(0)
	v_add_f32_e32 v146, v146, v147
	ds_bpermute_b32 v147, v161, v146
	s_waitcnt lgkmcnt(0)
	v_add_f32_e32 v146, v146, v147
	ds_bpermute_b32 v147, v162, v146
	s_waitcnt lgkmcnt(0)
	v_add_f32_e32 v146, v146, v147
	ds_bpermute_b32 v147, v163, v146
	s_waitcnt lgkmcnt(0)
; __device__ __forceinline__ void ln_stats(const f32x4 (&v)[4], float& mean, float& rstd) {
;     float s = 0.f;
; #pragma unroll
;     for (int j = 0; j < 4; ++j) s += (v[j].x + v[j].y) + (v[j].z + v[j].w);
;     mean = wsum(s) * (1.f / D);
;     float s2 = 0.f;
; #pragma unroll
;     for (int j = 0; j < 4; ++j) { const f32x4 d = v[j] - mean; s2 += (d.x * d.x + d.y * d.y) + (d.z * d.z + d.w * d.w); }
;     rstd = 1.f / sqrtf(wsum(s2) * (1.f / D) + LN_EPS);
; }
; __device__ __forceinline__ void deepnorm_r(f32x4 (&x)[4], const f32x4 (&y)[4], const f32x4 (&g1)[4], const f32x4 (&lg)[4], const f32x4 (&lb)[4]) {
;     ...
;     float mean, rstd; ln_stats(x, mean, rstd);
; #pragma unroll
;     for (int j = 0; j < 4; ++j) x[j] = (x[j] - mean) * rstd * lg[j] + lb[j];
; }
; __device__ __forceinline__ void phase_row1(const Frame& F, int l) {
;     ...
;             store_row_bf16((bf16*)(F.ws + WS_XB) + (size_t)row * D, lane, x);
;             ada_ln_r(x, sc1, sh);
	v_add_f32_e32 v146, v146, v147
	v_fmamk_f32 v146, v146, 0x3a800000, v226
	v_mul_f32_e32 v147, 0x4f800000, v146
	v_cmp_gt_f32_e32 vcc, s2, v146
	s_nop 1
	v_cndmask_b32_e32 v146, v146, v147, vcc
	v_sqrt_f32_e32 v147, v146
	s_nop 0
	v_add_u32_e32 v148, -1, v147
	v_fma_f32 v149, -v148, v147, v146
	v_cmp_ge_f32_e64 s[44:45], 0, v149
	v_add_u32_e32 v149, 1, v147
	s_nop 0
	v_cndmask_b32_e64 v148, v147, v148, s[44:45]
	v_fma_f32 v147, -v149, v147, v146
	v_cmp_lt_f32_e64 s[44:45], 0, v147
	s_nop 1
	v_cndmask_b32_e64 v147, v148, v149, s[44:45]
	v_mul_f32_e32 v148, 0x37800000, v147
	v_cndmask_b32_e32 v147, v147, v148, vcc
	v_cmp_class_f32_e32 vcc, v146, v227
	s_nop 1
	v_cndmask_b32_e32 v146, v147, v146, vcc
	v_div_scale_f32 v147, s[4:5], v146, v146, 1.0
	v_rcp_f32_e32 v148, v147
	s_nop 0
	v_fma_f32 v149, -v147, v148, 1.0
	v_fmac_f32_e32 v148, v149, v148
	v_div_scale_f32 v149, vcc, 1.0, v146, 1.0
	v_mul_f32_e32 v150, v149, v148
	v_fma_f32 v151, -v147, v150, v149
	v_fmac_f32_e32 v150, v151, v148
	v_fma_f32 v147, -v147, v150, v149
	v_div_fmas_f32 v147, v147, v148, v150
	v_div_fixup_f32 v146, v147, v146, 1.0
	v_pk_mul_f32 v[78:79], v[78:79], v[146:147] op_sel_hi:[1,0]
	v_pk_mul_f32 v[80:81], v[80:81], v[146:147] op_sel_hi:[1,0]
	v_pk_fma_f32 v[78:79], v[18:19], v[78:79], v[34:35]
	v_pk_fma_f32 v[80:81], v[20:21], v[80:81], v[36:37]
	v_pk_mul_f32 v[74:75], v[74:75], v[146:147] op_sel_hi:[1,0]
	v_pk_mul_f32 v[76:77], v[76:77], v[146:147] op_sel_hi:[1,0]
	v_pk_mul_f32 v[70:71], v[70:71], v[146:147] op_sel_hi:[1,0]
	v_pk_mul_f32 v[68:69], v[68:69], v[146:147] op_sel_hi:[1,0]
	v_pk_fma_f32 v[76:77], v[24:25], v[76:77], v[40:41]
	v_pk_fma_f32 v[74:75], v[22:23], v[74:75], v[38:39]
	v_pk_mul_f32 v[72:73], v[72:73], v[146:147] op_sel_hi:[1,0]
	v_pk_fma_f32 v[150:151], v[26:27], v[70:71], v[42:43]
	v_pk_mul_f32 v[66:67], v[66:67], v[146:147] op_sel_hi:[1,0]
	v_pk_fma_f32 v[146:147], v[32:33], v[68:69], v[48:49]
	v_pk_mov_b32 v[68:69], v[78:79], v[80:81] op_sel:[1,0]
	v_mov_b32_e32 v70, v78
	v_mov_b32_e32 v71, v81
	v_pk_fma_f32 v[148:149], v[28:29], v[72:73], v[44:45]
	v_pk_add_f32 v[68:69], v[68:69], v[70:71]
	v_pk_mov_b32 v[70:71], v[74:75], v[76:77] op_sel:[1,0]
	v_mov_b32_e32 v72, v74
	v_mov_b32_e32 v73, v77
	v_pk_add_f32 v[70:71], v[70:71], v[72:73]
	v_pk_fma_f32 v[66:67], v[30:31], v[66:67], v[46:47]
	v_add_f32_e32 v68, v68, v69
	v_pk_add_f32 v[70:71], v[70:71], v[70:71] op_sel_hi:[0,1]
	v_add_f32_e32 v69, 0, v68
	v_add_f32_e32 v73, v150, v151
	v_add_f32_e32 v153, v148, v149
	v_mov_b32_e32 v72, v66
	v_mov_b32_e32 v152, v67
	v_mov_b32_e32 v70, v146
	v_mov_b32_e32 v68, v147
	v_pk_add_f32 v[72:73], v[72:73], v[152:153]
	v_pk_add_f32 v[68:69], v[70:71], v[68:69]
	v_cvt_pk_bf16_f32 v152, v78, v79
	v_cvt_pk_bf16_f32 v153, v80, v81
	v_cvt_pk_bf16_f32 v164, v74, v75
	v_cvt_pk_bf16_f32 v165, v76, v77
	v_cvt_pk_bf16_f32 v166, v150, v151
	s_nop 0
	v_pk_add_f32 v[68:69], v[72:73], v[68:69]
	v_cvt_pk_bf16_f32 v167, v148, v149
	v_cvt_pk_bf16_f32 v168, v66, v67
	v_cvt_pk_bf16_f32 v169, v146, v147
	s_nop 0
	v_add_f32_e32 v68, v68, v69
	ds_bpermute_b32 v69, v135, v68
	s_waitcnt lgkmcnt(0)
	v_add_f32_e32 v68, v68, v69
	ds_bpermute_b32 v69, v159, v68
	s_waitcnt lgkmcnt(0)
	v_add_f32_e32 v68, v68, v69
	ds_bpermute_b32 v69, v160, v68
	s_waitcnt lgkmcnt(0)
	v_add_f32_e32 v68, v68, v69
	ds_bpermute_b32 v69, v161, v68
	s_waitcnt lgkmcnt(0)
	v_add_f32_e32 v68, v68, v69
	ds_bpermute_b32 v69, v162, v68
	s_waitcnt lgkmcnt(0)
	v_add_f32_e32 v68, v68, v69
	ds_bpermute_b32 v69, v163, v68
	s_waitcnt lgkmcnt(0)
	v_add_f32_e32 v172, v68, v69
	v_fmamk_f32 v79, v172, 0xba800000, v79
	v_fmac_f32_e32 v78, 0xba800000, v172
	v_fmamk_f32 v81, v172, 0xba800000, v81
	v_fmac_f32_e32 v80, 0xba800000, v172
	v_pk_mul_f32 v[68:69], v[80:81], v[80:81]
	v_pk_mul_f32 v[70:71], v[78:79], v[78:79]
	v_fmamk_f32 v75, v172, 0xba800000, v75
	v_pk_mov_b32 v[72:73], v[70:71], v[68:69] op_sel:[1,0]
	v_mov_b32_e32 v71, v69
	v_pk_add_f32 v[68:69], v[72:73], v[70:71]
	v_fmac_f32_e32 v74, 0xba800000, v172
	v_fmamk_f32 v77, v172, 0xba800000, v77
	v_fmac_f32_e32 v76, 0xba800000, v172
	v_pk_add_f32 v[68:69], v[68:69], v[68:69] op_sel_hi:[0,1]
	v_pk_mul_f32 v[70:71], v[76:77], v[76:77]
	v_pk_mul_f32 v[72:73], v[74:75], v[74:75]
	v_fmac_f32_e32 v150, 0xba800000, v172
	v_pk_mov_b32 v[170:171], v[72:73], v[70:71] op_sel:[1,0]
	v_mov_b32_e32 v73, v71
	v_fmamk_f32 v151, v172, 0xba800000, v151
	v_fmac_f32_e32 v148, 0xba800000, v172
	v_mul_f32_e32 v68, v150, v150
	v_pk_add_f32 v[70:71], v[170:171], v[72:73]
	v_fmamk_f32 v149, v172, 0xba800000, v149
	v_pk_fma_f32 v[72:73], v[150:151], v[150:151], v[68:69] op_sel_hi:[1,1,0]
	v_mul_f32_e32 v68, v148, v148
	v_pk_add_f32 v[70:71], v[70:71], v[70:71] op_sel_hi:[0,1]
	v_pk_fma_f32 v[170:171], v[148:149], v[148:149], v[68:69] op_sel_hi:[1,1,0]
	v_fmamk_f32 v147, v172, 0xba800000, v147
	v_fmac_f32_e32 v146, 0xba800000, v172
	v_fmamk_f32 v67, v172, 0xba800000, v67
	v_fmac_f32_e32 v66, 0xba800000, v172
	v_mul_f32_e32 v72, v66, v66
	v_mul_f32_e32 v170, v67, v67
	v_mul_f32_e32 v68, v146, v146
	v_mul_f32_e32 v70, v147, v147
	v_pk_add_f32 v[72:73], v[72:73], v[170:171]
	v_pk_add_f32 v[68:69], v[68:69], v[70:71]
	s_nop 0
	v_pk_add_f32 v[68:69], v[72:73], v[68:69]
	s_nop 0
	v_add_f32_e32 v68, v68, v69
	ds_bpermute_b32 v69, v135, v68
	s_waitcnt lgkmcnt(0)
	v_add_f32_e32 v68, v68, v69
	ds_bpermute_b32 v69, v159, v68
	s_waitcnt lgkmcnt(0)
	v_add_f32_e32 v68, v68, v69
	ds_bpermute_b32 v69, v160, v68
	s_waitcnt lgkmcnt(0)
	v_add_f32_e32 v68, v68, v69
	ds_bpermute_b32 v69, v161, v68
	s_waitcnt lgkmcnt(0)
; __device__ __forceinline__ unsigned pk4_fp8(f32x4 v) { int r = 0; r = __builtin_amdgcn_cvt_pk_fp8_f32(v.x, v.y, r, false); r = __builtin_amdgcn_cvt_pk_fp8_f32(v.z, v.w, r, true); return (unsigned)r; }
; __device__ __forceinline__ void phase_row1(const Frame& F, int l) {
;     ...
;             deepnorm_r(x, y, g1, vlg, vlb);
;             store_row_bf16((bf16*)(F.ws + WS_XB) + (size_t)row * D, lane, x);
;             ada_ln_r(x, sc1, sh);
;             store_row(H32 + (size_t)row * D, lane, x);
;             {
;                 float am = 0.f;
; #pragma unroll
;                 for (int j = 0; j < 4; ++j) am = fmaxf(am, fmaxf(fmaxf(fabsf(x[j].x), fabsf(x[j].y)), fmaxf(fabsf(x[j].z), fabsf(x[j].w))));
;                 am = fmaxf(wmaxf(am), 1e-20f);
;                 const float qs = 224.f / am;
;                 unsigned char* hq = (unsigned char*)(F.ws + WS_HQ) + (size_t)row * D;
; #pragma unroll
;                 for (int j = 0; j < 4; ++j) *(unsigned*)(hq + 256 * j + 4 * lane) = pk4_fp8(x[j] * qs);
;                 if (lane == 0) ((float*)(F.ws + WS_HS))[row] = am * (1.f / 224.f);
;             }
	v_add_f32_e32 v68, v68, v69
	ds_bpermute_b32 v69, v162, v68
	s_waitcnt lgkmcnt(0)
	v_add_f32_e32 v68, v68, v69
	ds_bpermute_b32 v69, v163, v68
	s_waitcnt lgkmcnt(0)
	v_add_f32_e32 v68, v68, v69
	v_fmamk_f32 v68, v68, 0x3a800000, v226
	v_mul_f32_e32 v69, 0x4f800000, v68
	v_cmp_gt_f32_e32 vcc, s2, v68
	s_nop 1
	v_cndmask_b32_e32 v68, v68, v69, vcc
	v_sqrt_f32_e32 v69, v68
	s_nop 0
	v_add_u32_e32 v70, -1, v69
	v_fma_f32 v71, -v70, v69, v68
	v_cmp_ge_f32_e64 s[44:45], 0, v71
	v_add_u32_e32 v71, 1, v69
	s_nop 0
	v_cndmask_b32_e64 v70, v69, v70, s[44:45]
	v_fma_f32 v69, -v71, v69, v68
	v_cmp_lt_f32_e64 s[44:45], 0, v69
	s_nop 1
	v_cndmask_b32_e64 v69, v70, v71, s[44:45]
	v_mul_f32_e32 v70, 0x37800000, v69
	v_cndmask_b32_e32 v69, v69, v70, vcc
	v_cmp_class_f32_e32 vcc, v68, v227
	s_nop 1
	v_cndmask_b32_e32 v68, v69, v68, vcc
	v_div_scale_f32 v69, s[4:5], v68, v68, 1.0
	v_rcp_f32_e32 v70, v69
	s_lshl_b64 s[4:5], s[26:27], 10
	v_fma_f32 v71, -v69, v70, 1.0
	v_fmac_f32_e32 v70, v71, v70
	v_div_scale_f32 v71, vcc, 1.0, v68, 1.0
	v_mul_f32_e32 v72, v71, v70
	v_fma_f32 v73, -v69, v72, v71
	v_fmac_f32_e32 v72, v73, v70
	v_fma_f32 v69, -v69, v72, v71
	v_div_fmas_f32 v69, v69, v70, v72
	v_div_fixup_f32 v170, v69, v68, 1.0
	v_pk_mul_f32 v[70:71], v[80:81], v[170:171] op_sel_hi:[1,0]
	v_pk_mul_f32 v[72:73], v[74:75], v[170:171] op_sel_hi:[1,0]
	v_pk_mul_f32 v[74:75], v[76:77], v[170:171] op_sel_hi:[1,0]
	v_pk_mul_f32 v[68:69], v[78:79], v[170:171] op_sel_hi:[1,0]
	v_pk_fma_f32 v[70:71], v[112:113], v[70:71], v[60:61]
	v_pk_fma_f32 v[74:75], v[108:109], v[74:75], v[52:53]
	v_pk_mul_f32 v[66:67], v[66:67], v[170:171] op_sel_hi:[1,0]
	v_pk_fma_f32 v[68:69], v[110:111], v[68:69], v[58:59]
	v_pk_fma_f32 v[72:73], v[106:107], v[72:73], v[50:51]
	v_pk_mul_f32 v[78:79], v[148:149], v[170:171] op_sel_hi:[1,0]
	v_pk_mul_f32 v[80:81], v[146:147], v[170:171] op_sel_hi:[1,0]
	v_pk_fma_f32 v[146:147], v[98:99], v[66:67], v[62:63]
	v_max_f32_e64 v66, |v70|, |v71|
	v_max_f32_e64 v67, |v74|, |v75|
	v_pk_mul_f32 v[76:77], v[150:151], v[170:171] op_sel_hi:[1,0]
	v_pk_fma_f32 v[78:79], v[104:105], v[78:79], v[56:57]
	v_pk_fma_f32 v[148:149], v[100:101], v[80:81], v[64:65]
	v_max3_f32 v66, |v68|, |v69|, v66
	v_max3_f32 v67, |v72|, |v73|, v67
	v_pk_fma_f32 v[76:77], v[102:103], v[76:77], v[54:55]
	v_max3_f32 v66, v66, 0, v67
	v_max_f32_e64 v67, |v78|, |v79|
	v_max_f32_e64 v80, |v148|, |v149|
	v_max3_f32 v67, |v76|, |v77|, v67
	v_max3_f32 v80, |v146|, |v147|, v80
	v_max3_f32 v66, v66, v67, v80
	ds_bpermute_b32 v67, v135, v66
	s_waitcnt lgkmcnt(0)
	v_max_f32_e32 v67, v67, v67
	v_max_f32_e32 v66, v66, v67
	ds_bpermute_b32 v67, v159, v66
	s_waitcnt lgkmcnt(0)
	v_max_f32_e32 v67, v67, v67
	v_max_f32_e32 v66, v66, v67
	ds_bpermute_b32 v67, v160, v66
	s_waitcnt lgkmcnt(0)
	v_max_f32_e32 v67, v67, v67
	v_max_f32_e32 v66, v66, v67
	ds_bpermute_b32 v67, v161, v66
	s_waitcnt lgkmcnt(0)
	v_max_f32_e32 v67, v67, v67
	v_max_f32_e32 v80, v66, v67
	ds_bpermute_b32 v81, v162, v80
	v_lshl_add_u64 v[66:67], v[116:117], 0, s[30:31]
	global_store_dwordx2 v[66:67], v[152:153], off nt
	global_store_dwordx2 v[66:67], v[164:165], off offset:512 nt
	global_store_dwordx2 v[66:67], v[166:167], off offset:1024 nt
	global_store_dwordx2 v[66:67], v[168:169], off offset:1536 nt
	s_lshl_b64 s[30:31], s[26:27], 12
	s_waitcnt lgkmcnt(0)
	v_max_f32_e32 v81, v81, v81
	v_max_f32_e32 v150, v80, v81
	ds_bpermute_b32 v151, v163, v150
	v_lshl_add_u64 v[80:81], v[114:115], 0, s[30:31]
	global_store_dwordx4 v[80:81], v[68:71], off
	global_store_dwordx4 v[80:81], v[72:75], off offset:1024
	global_store_dwordx4 v[80:81], v[76:79], off offset:2048
	global_store_dwordx4 v[80:81], v[146:149], off offset:3072
	s_waitcnt lgkmcnt(0)
	v_max3_f32 v66, v150, v151, s7
	v_div_scale_f32 v67, s[30:31], v66, v66, s20
	v_rcp_f32_e32 v150, v67
	s_nop 0
	v_fma_f32 v80, -v67, v150, 1.0
	v_fmac_f32_e32 v150, v80, v150
	v_div_scale_f32 v80, vcc, s20, v66, s20
	v_mul_f32_e32 v81, v80, v150
	v_fma_f32 v151, -v67, v81, v80
	v_fmac_f32_e32 v81, v151, v150
	v_fma_f32 v67, -v67, v81, v80
	v_div_fmas_f32 v67, v67, v150, v81
	v_div_fixup_f32 v80, v67, v66, s20
	v_pk_mul_f32 v[68:69], v[68:69], v[80:81] op_sel_hi:[1,0]
	v_mov_b32_e32 v67, 0
	v_cvt_pk_fp8_f32 v67, v68, v69
	v_pk_mul_f32 v[68:69], v[72:73], v[80:81] op_sel_hi:[1,0]
	v_mov_b32_e32 v72, 0
	v_cvt_pk_fp8_f32 v72, v68, v69
	v_pk_mul_f32 v[68:69], v[70:71], v[80:81] op_sel_hi:[1,0]
	v_mov_b32_e32 v70, 0
	v_cvt_pk_fp8_f32 v67, v68, v69 op_sel:[0,0,1]
	v_pk_mul_f32 v[68:69], v[74:75], v[80:81] op_sel_hi:[1,0]
	v_mov_b32_e32 v71, 0
	v_cvt_pk_fp8_f32 v72, v68, v69 op_sel:[0,0,1]
	v_pk_mul_f32 v[68:69], v[76:77], v[80:81] op_sel_hi:[1,0]
	v_lshl_add_u64 v[150:151], v[120:121], 0, s[4:5]
	v_cvt_pk_fp8_f32 v70, v68, v69
	v_pk_mul_f32 v[68:69], v[146:147], v[80:81] op_sel_hi:[1,0]
	s_nop 0
	v_cvt_pk_fp8_f32 v71, v68, v69
	v_pk_mul_f32 v[68:69], v[78:79], v[80:81] op_sel_hi:[1,0]
	s_nop 0
	v_cvt_pk_fp8_f32 v70, v68, v69 op_sel:[0,0,1]
	v_pk_mul_f32 v[68:69], v[148:149], v[80:81] op_sel_hi:[1,0]
	s_nop 0
	v_cvt_pk_fp8_f32 v71, v68, v69 op_sel:[0,0,1]
	global_store_dword v[150:151], v67, off
	global_store_dword v[150:151], v72, off offset:256
	global_store_dword v[150:151], v70, off offset:512
	global_store_dword v[150:151], v71, off offset:768
	s_and_saveexec_b64 s[4:5], s[0:1]
	s_cbranch_execz .LBB0_2149
	s_lshl_b64 s[26:27], s[26:27], 2
	s_add_u32 s26, s54, s26
	v_mul_f32_e32 v66, 0x3b924925, v66
	s_addc_u32 s27, s55, s27
	global_store_dword v199, v66, s[26:27]

; __device__ __forceinline__ f32x4 bf4lo(u32x4 q) { return (f32x4){__uint_as_float(q.x << 16), __uint_as_float(q.x & 0xffff0000u), __uint_as_float(q.y << 16), __uint_as_float(q.y & 0xffff0000u)}; }
; __device__ __forceinline__ f32x4 bf4hi(u32x4 q) { return (f32x4){__uint_as_float(q.z << 16), __uint_as_float(q.z & 0xffff0000u), __uint_as_float(q.w << 16), __uint_as_float(q.w & 0xffff0000u)}; }
; __device__ __forceinline__ void deepnorm_r(f32x4 (&x)[4], const f32x4 (&y)[4], const f32x4 (&g1)[4], const f32x4 (&lg)[4], const f32x4 (&lb)[4]) {
; #pragma unroll
;     for (int j = 0; j < 4; ++j) x[j] = ALPHA * x[j] + g1[j] * y[j];
; __device__ __forceinline__ void phase_row2(const Frame& F, int l) {
;     ...
;         for (int i = 0; i < 8; ++i) {
;             const int row = row0 + i;
;             if (i + 1 < 8) { const bf16* yk = (const bf16*)(F.ws + WS_YK) + (size_t)(row + 1) * 4 * D + 8 * lane;
; #pragma unroll
;                 for (int j2 = 0; j2 < 2; ++j2) { nxb[j2] = *(const u32x4*)(XB + (size_t)(row + 1) * D + 512 * j2 + 8 * lane);
; #pragma unroll
;                     for (int k = 0; k < 4; ++k) ny[k][j2] = *(const u32x4*)(yk + k * D + 512 * j2); } }
;             f32x4 x[4], y[4];
; #pragma unroll
;             for (int j2 = 0; j2 < 2; ++j2) { x[2 * j2] = bf4lo(cxb[j2]); x[2 * j2 + 1] = bf4hi(cxb[j2]);
;                 y[2 * j2] = (bf4lo(cy[0][j2]) + bf4lo(cy[1][j2])) + (bf4lo(cy[2][j2]) + bf4lo(cy[3][j2]));
;                 y[2 * j2 + 1] = (bf4hi(cy[0][j2]) + bf4hi(cy[1][j2])) + (bf4hi(cy[2][j2]) + bf4hi(cy[3][j2])); }
;             deepnorm_r(x, y, g1, lg, lb);
.LBB0_2427:
	s_waitcnt vmcnt(7)
	v_lshlrev_b32_e32 v94, 16, v82
	v_and_b32_e32 v95, 0xffff0000, v82
	v_lshlrev_b32_e32 v82, 16, v83
	v_and_b32_e32 v83, 0xffff0000, v83
	s_waitcnt vmcnt(5)
	v_lshlrev_b32_e32 v96, 16, v78
	v_and_b32_e32 v97, 0xffff0000, v78
	v_lshlrev_b32_e32 v78, 16, v79
	v_and_b32_e32 v79, 0xffff0000, v79
	v_pk_add_f32 v[94:95], v[96:97], v[94:95]
	v_pk_add_f32 v[78:79], v[78:79], v[82:83]
	s_waitcnt vmcnt(3)
	v_lshlrev_b32_e32 v82, 16, v74
	v_and_b32_e32 v83, 0xffff0000, v74
	v_lshlrev_b32_e32 v74, 16, v75
	v_and_b32_e32 v75, 0xffff0000, v75
	s_waitcnt vmcnt(1)
	v_lshlrev_b32_e32 v96, 16, v70
	v_and_b32_e32 v97, 0xffff0000, v70
	v_lshlrev_b32_e32 v70, 16, v71
	v_and_b32_e32 v71, 0xffff0000, v71
	v_pk_add_f32 v[82:83], v[96:97], v[82:83]
	v_pk_add_f32 v[70:71], v[70:71], v[74:75]
	v_pk_add_f32 v[74:75], v[82:83], v[94:95]
	v_pk_add_f32 v[70:71], v[70:71], v[78:79]
	v_lshlrev_b32_e32 v78, 16, v84
	v_and_b32_e32 v79, 0xffff0000, v84
	v_lshlrev_b32_e32 v82, 16, v85
	v_and_b32_e32 v83, 0xffff0000, v85
	v_lshlrev_b32_e32 v84, 16, v80
	v_and_b32_e32 v85, 0xffff0000, v80
	v_lshlrev_b32_e32 v80, 16, v81
	v_and_b32_e32 v81, 0xffff0000, v81
	v_pk_add_f32 v[78:79], v[84:85], v[78:79]
	v_pk_add_f32 v[80:81], v[80:81], v[82:83]
	v_lshlrev_b32_e32 v82, 16, v76
	v_and_b32_e32 v83, 0xffff0000, v76
	v_lshlrev_b32_e32 v84, 16, v72
	v_and_b32_e32 v85, 0xffff0000, v72
	v_lshlrev_b32_e32 v76, 16, v77
	v_and_b32_e32 v77, 0xffff0000, v77
	v_lshlrev_b32_e32 v72, 16, v73
	v_and_b32_e32 v73, 0xffff0000, v73
	v_pk_add_f32 v[82:83], v[84:85], v[82:83]
	v_pk_add_f32 v[72:73], v[72:73], v[76:77]
	v_pk_add_f32 v[76:77], v[82:83], v[78:79]
	v_lshlrev_b32_e32 v82, 16, v62
	v_and_b32_e32 v83, 0xffff0000, v62
	v_lshlrev_b32_e32 v62, 16, v63
	v_and_b32_e32 v63, 0xffff0000, v63
	v_lshlrev_b32_e32 v84, 16, v58
	v_and_b32_e32 v85, 0xffff0000, v58
	v_lshlrev_b32_e32 v58, 16, v59
	v_and_b32_e32 v59, 0xffff0000, v59
	v_pk_add_f32 v[82:83], v[84:85], v[82:83]
	v_pk_add_f32 v[58:59], v[58:59], v[62:63]
	v_lshlrev_b32_e32 v62, 16, v54
	v_and_b32_e32 v63, 0xffff0000, v54
	v_lshlrev_b32_e32 v54, 16, v55
	v_and_b32_e32 v55, 0xffff0000, v55
	s_waitcnt vmcnt(0)
	v_lshlrev_b32_e32 v84, 16, v50
	v_and_b32_e32 v85, 0xffff0000, v50
	v_lshlrev_b32_e32 v50, 16, v51
	v_and_b32_e32 v51, 0xffff0000, v51
	v_pk_add_f32 v[62:63], v[84:85], v[62:63]
	v_pk_add_f32 v[50:51], v[50:51], v[54:55]
	v_pk_add_f32 v[54:55], v[62:63], v[82:83]
	v_pk_add_f32 v[50:51], v[50:51], v[58:59]
	v_lshlrev_b32_e32 v58, 16, v64
	v_and_b32_e32 v59, 0xffff0000, v64
	v_lshlrev_b32_e32 v62, 16, v65
	v_and_b32_e32 v63, 0xffff0000, v65
	v_lshlrev_b32_e32 v64, 16, v60
	v_and_b32_e32 v65, 0xffff0000, v60
	v_lshlrev_b32_e32 v60, 16, v61
	v_and_b32_e32 v61, 0xffff0000, v61
	v_pk_add_f32 v[58:59], v[64:65], v[58:59]
	v_pk_add_f32 v[60:61], v[60:61], v[62:63]
	v_lshlrev_b32_e32 v62, 16, v56
	v_and_b32_e32 v63, 0xffff0000, v56
	v_lshlrev_b32_e32 v56, 16, v57
	v_and_b32_e32 v57, 0xffff0000, v57
	v_lshlrev_b32_e32 v64, 16, v52
	v_and_b32_e32 v65, 0xffff0000, v52
	v_lshlrev_b32_e32 v52, 16, v53
	v_and_b32_e32 v53, 0xffff0000, v53
	v_pk_add_f32 v[62:63], v[64:65], v[62:63]
	v_pk_add_f32 v[52:53], v[52:53], v[56:57]
	v_lshlrev_b32_e32 v90, 16, v86
	v_and_b32_e32 v91, 0xffff0000, v86
	v_lshlrev_b32_e32 v86, 16, v87
	v_and_b32_e32 v87, 0xffff0000, v87
	v_pk_add_f32 v[72:73], v[72:73], v[80:81]
	v_lshlrev_b32_e32 v78, 16, v66
	v_and_b32_e32 v79, 0xffff0000, v66
	v_lshlrev_b32_e32 v66, 16, v67
	v_and_b32_e32 v67, 0xffff0000, v67
	v_pk_add_f32 v[52:53], v[52:53], v[60:61]
	v_pk_add_f32 v[56:57], v[62:63], v[58:59]
	v_pk_mul_f32 v[58:59], v[150:151], v[74:75]
	v_pk_mul_f32 v[60:61], v[148:149], v[70:71]
	v_pk_mul_f32 v[50:51], v[140:141], v[50:51]
	v_lshlrev_b32_e32 v92, 16, v88
	v_and_b32_e32 v93, 0xffff0000, v88
	v_lshlrev_b32_e32 v88, 16, v89
	v_and_b32_e32 v89, 0xffff0000, v89
	v_lshlrev_b32_e32 v80, 16, v68
	v_and_b32_e32 v81, 0xffff0000, v68
	v_lshlrev_b32_e32 v68, 16, v69
	v_and_b32_e32 v69, 0xffff0000, v69
	v_pk_fma_f32 v[94:95], v[86:87], s[16:17], v[60:61] op_sel_hi:[1,0,1]
	v_pk_fma_f32 v[90:91], v[90:91], s[16:17], v[58:59] op_sel_hi:[1,0,1]
	v_pk_mul_f32 v[58:59], v[146:147], v[76:77]
	v_pk_mul_f32 v[60:61], v[144:145], v[72:73]
	v_pk_fma_f32 v[100:101], v[66:67], s[16:17], v[50:51] op_sel_hi:[1,0,1]
	v_pk_mul_f32 v[50:51], v[138:139], v[56:57]
	v_pk_mul_f32 v[52:53], v[136:137], v[52:53]
	v_pk_fma_f32 v[96:97], v[88:89], s[16:17], v[60:61] op_sel_hi:[1,0,1]
	v_pk_fma_f32 v[98:99], v[92:93], s[16:17], v[58:59] op_sel_hi:[1,0,1]
	v_pk_mul_f32 v[54:55], v[142:143], v[54:55]
	v_pk_fma_f32 v[104:105], v[68:69], s[16:17], v[52:53] op_sel_hi:[1,0,1]
	v_pk_fma_f32 v[156:157], v[80:81], s[16:17], v[50:51] op_sel_hi:[1,0,1]
	v_pk_mov_b32 v[50:51], v[90:91], v[94:95] op_sel:[1,0]
	v_mov_b32_e32 v52, v90
	v_mov_b32_e32 v53, v95
	v_pk_fma_f32 v[102:103], v[78:79], s[16:17], v[54:55] op_sel_hi:[1,0,1]
	v_pk_add_f32 v[50:51], v[50:51], v[52:53]
	v_pk_mov_b32 v[52:53], v[98:99], v[96:97] op_sel:[1,0]
	v_mov_b32_e32 v54, v98
	v_mov_b32_e32 v55, v97
	v_pk_add_f32 v[52:53], v[52:53], v[54:55]
	v_add_f32_e32 v50, v50, v51
	v_pk_add_f32 v[52:53], v[52:53], v[52:53] op_sel_hi:[0,1]
	v_add_f32_e32 v51, 0, v50
	v_add_f32_e32 v55, v102, v103
	v_add_f32_e32 v57, v100, v101
	v_mov_b32_e32 v54, v156
	v_mov_b32_e32 v56, v157
	v_mov_b32_e32 v52, v104
	v_mov_b32_e32 v50, v105
	v_pk_add_f32 v[54:55], v[54:55], v[56:57]
	v_pk_add_f32 v[50:51], v[52:53], v[50:51]
	s_add_i32 s26, s8, s10
	v_pk_add_f32 v[50:51], v[54:55], v[50:51]
	s_add_i32 s0, s26, 1
	v_add_f32_e32 v50, v50, v51
	ds_bpermute_b32 v51, v1, v50
	s_ashr_i32 s1, s0, 31
	s_lshl_b64 s[30:31], s[0:1], 13
	s_lshl_b64 s[0:1], s[0:1], 11
	v_lshl_add_u64 v[52:53], v[108:109], 0, s[0:1]
	s_waitcnt lgkmcnt(0)
; __device__ __forceinline__ void deepnorm_r(f32x4 (&x)[4], const f32x4 (&y)[4], const f32x4 (&g1)[4], const f32x4 (&lg)[4], const f32x4 (&lb)[4]) {
;     ...
;     float mean, rstd; ln_stats(x, mean, rstd);
; #pragma unroll
;     for (int j = 0; j < 4; ++j) x[j] = (x[j] - mean) * rstd * lg[j] + lb[j];
; }
; __device__ __forceinline__ void phase_row2(const Frame& F, int l) {
;     ...
;             if (i + 1 < 8) { const bf16* yk = (const bf16*)(F.ws + WS_YK) + (size_t)(row + 1) * 4 * D + 8 * lane;
; #pragma unroll
;                 for (int j2 = 0; j2 < 2; ++j2) { nxb[j2] = *(const u32x4*)(XB + (size_t)(row + 1) * D + 512 * j2 + 8 * lane);
; #pragma unroll
;                     for (int k = 0; k < 4; ++k) ny[k][j2] = *(const u32x4*)(yk + k * D + 512 * j2); } }
	v_add_f32_e32 v50, v50, v51
	ds_bpermute_b32 v51, v107, v50
	s_waitcnt lgkmcnt(0)
	v_add_f32_e32 v50, v50, v51
	ds_bpermute_b32 v51, v152, v50
	s_waitcnt lgkmcnt(0)
	v_add_f32_e32 v50, v50, v51
	ds_bpermute_b32 v51, v153, v50
	s_waitcnt lgkmcnt(0)
	v_add_f32_e32 v54, v50, v51
	ds_bpermute_b32 v55, v154, v54
	v_lshl_add_u64 v[50:51], v[112:113], 0, s[30:31]
	v_add_co_u32_e32 v92, vcc, s77, v50
	s_waitcnt lgkmcnt(0)
	v_add_f32_e32 v54, v54, v55
	ds_bpermute_b32 v55, v155, v54
	v_addc_co_u32_e32 v93, vcc, 0, v51, vcc
	s_waitcnt lgkmcnt(0)
	v_add_f32_e32 v62, v54, v55
	v_fmamk_f32 v91, v62, 0xba800000, v91
	v_fmac_f32_e32 v90, 0xba800000, v62
	v_fmamk_f32 v95, v62, 0xba800000, v95
	v_fmac_f32_e32 v94, 0xba800000, v62
	v_pk_mul_f32 v[54:55], v[94:95], v[94:95]
	v_pk_mul_f32 v[56:57], v[90:91], v[90:91]
	v_fmamk_f32 v99, v62, 0xba800000, v99
	v_pk_mov_b32 v[58:59], v[56:57], v[54:55] op_sel:[1,0]
	v_mov_b32_e32 v57, v55
	v_pk_add_f32 v[54:55], v[58:59], v[56:57]
	v_fmac_f32_e32 v98, 0xba800000, v62
	v_fmamk_f32 v97, v62, 0xba800000, v97
	v_fmac_f32_e32 v96, 0xba800000, v62
	v_pk_add_f32 v[54:55], v[54:55], v[54:55] op_sel_hi:[0,1]
	v_pk_mul_f32 v[56:57], v[96:97], v[96:97]
	v_pk_mul_f32 v[58:59], v[98:99], v[98:99]
	v_fmac_f32_e32 v102, 0xba800000, v62
	v_pk_mov_b32 v[60:61], v[58:59], v[56:57] op_sel:[1,0]
	v_mov_b32_e32 v59, v57
	v_fmamk_f32 v103, v62, 0xba800000, v103
	v_fmac_f32_e32 v100, 0xba800000, v62
	v_mul_f32_e32 v54, v102, v102
	v_pk_add_f32 v[56:57], v[60:61], v[58:59]
	v_fmamk_f32 v101, v62, 0xba800000, v101
	v_pk_fma_f32 v[58:59], v[102:103], v[102:103], v[54:55] op_sel_hi:[1,1,0]
	v_mul_f32_e32 v54, v100, v100
	v_pk_add_f32 v[56:57], v[56:57], v[56:57] op_sel_hi:[0,1]
	v_pk_fma_f32 v[60:61], v[100:101], v[100:101], v[54:55] op_sel_hi:[1,1,0]
	v_fmamk_f32 v105, v62, 0xba800000, v105
	v_fmac_f32_e32 v104, 0xba800000, v62
	v_fmamk_f32 v157, v62, 0xba800000, v157
	v_fmac_f32_e32 v156, 0xba800000, v62
	v_mul_f32_e32 v58, v156, v156
	v_mul_f32_e32 v60, v157, v157
	v_mul_f32_e32 v54, v104, v104
	v_mul_f32_e32 v56, v105, v105
	v_pk_add_f32 v[58:59], v[58:59], v[60:61]
	v_pk_add_f32 v[54:55], v[54:55], v[56:57]
	global_load_dwordx4 v[86:89], v[52:53], off nt
	global_load_dwordx4 v[66:69], v[52:53], off offset:1024 nt
	global_load_dwordx4 v[82:85], v[50:51], off nt
	global_load_dwordx4 v[62:65], v[50:51], off offset:1024 nt
	v_pk_add_f32 v[54:55], v[58:59], v[54:55]
	s_nop 0
	v_add_f32_e32 v54, v54, v55
	ds_bpermute_b32 v55, v1, v54
	s_waitcnt lgkmcnt(0)
	v_add_f32_e32 v52, v54, v55
	ds_bpermute_b32 v53, v107, v52
	global_load_dwordx4 v[78:81], v[50:51], off offset:2048 nt
	global_load_dwordx4 v[58:61], v[50:51], off offset:3072 nt
	global_load_dwordx4 v[74:77], v[92:93], off nt
	global_load_dwordx4 v[54:57], v[92:93], off offset:1024 nt
	s_waitcnt lgkmcnt(0)
	v_add_f32_e32 v158, v52, v53
	global_load_dwordx4 v[70:73], v[92:93], off offset:2048 nt
	global_load_dwordx4 v[50:53], v[92:93], off offset:3072 nt
	ds_bpermute_b32 v159, v152, v158
	s_waitcnt lgkmcnt(0)
	v_add_f32_e32 v92, v158, v159
	ds_bpermute_b32 v93, v153, v92
	s_waitcnt lgkmcnt(0)
	v_add_f32_e32 v92, v92, v93
	ds_bpermute_b32 v93, v154, v92
	s_waitcnt lgkmcnt(0)
	v_add_f32_e32 v92, v92, v93
	ds_bpermute_b32 v93, v155, v92
	s_waitcnt lgkmcnt(0)
	v_add_f32_e32 v92, v92, v93
	v_fmamk_f32 v92, v92, 0x3a800000, v226
	v_mul_f32_e32 v93, 0x4f800000, v92
	v_cmp_gt_f32_e32 vcc, s2, v92
	s_nop 1
	v_cndmask_b32_e32 v92, v92, v93, vcc
	v_sqrt_f32_e32 v93, v92
	s_nop 0
	v_add_u32_e32 v158, -1, v93
	v_fma_f32 v159, -v158, v93, v92
	v_cmp_ge_f32_e64 s[0:1], 0, v159
	v_add_u32_e32 v159, 1, v93
	s_nop 0
	v_cndmask_b32_e64 v158, v93, v158, s[0:1]
	v_fma_f32 v93, -v159, v93, v92
	v_cmp_lt_f32_e64 s[0:1], 0, v93
	s_nop 1
	v_cndmask_b32_e64 v93, v158, v159, s[0:1]
	v_mul_f32_e32 v158, 0x37800000, v93
	v_cndmask_b32_e32 v93, v93, v158, vcc
	v_cmp_class_f32_e32 vcc, v92, v227
	s_nop 1
	v_cndmask_b32_e32 v92, v93, v92, vcc
	v_div_scale_f32 v93, s[0:1], v92, v92, 1.0
	v_rcp_f32_e32 v158, v93
	s_mov_b64 s[0:1], -1
	v_fma_f32 v159, -v93, v158, 1.0
	v_fmac_f32_e32 v158, v159, v158
	v_div_scale_f32 v159, vcc, 1.0, v92, 1.0
	v_mul_f32_e32 v160, v159, v158
	v_fma_f32 v161, -v93, v160, v159
	v_fmac_f32_e32 v160, v161, v158
	v_fma_f32 v93, -v93, v160, v159
	v_div_fmas_f32 v93, v93, v158, v160
	v_div_fixup_f32 v158, v93, v92, 1.0
	v_pk_mul_f32 v[90:91], v[90:91], v[158:159] op_sel_hi:[1,0]
	v_pk_mul_f32 v[92:93], v[94:95], v[158:159] op_sel_hi:[1,0]
	v_pk_mul_f32 v[94:95], v[98:99], v[158:159] op_sel_hi:[1,0]
	v_pk_mul_f32 v[96:97], v[96:97], v[158:159] op_sel_hi:[1,0]
	v_pk_mul_f32 v[98:99], v[102:103], v[158:159] op_sel_hi:[1,0]
	v_pk_mul_f32 v[100:101], v[100:101], v[158:159] op_sel_hi:[1,0]
	v_pk_mul_f32 v[102:103], v[156:157], v[158:159] op_sel_hi:[1,0]
	v_pk_mul_f32 v[104:105], v[104:105], v[158:159] op_sel_hi:[1,0]
	v_pk_fma_f32 v[92:93], v[44:45], v[92:93], v[48:49]
	v_pk_fma_f32 v[90:91], v[42:43], v[90:91], v[46:47]
	v_pk_fma_f32 v[96:97], v[36:37], v[96:97], v[40:41]
	v_pk_fma_f32 v[94:95], v[34:35], v[94:95], v[38:39]
	v_pk_fma_f32 v[100:101], v[28:29], v[100:101], v[32:33]
	v_pk_fma_f32 v[98:99], v[26:27], v[98:99], v[30:31]
	v_pk_fma_f32 v[104:105], v[20:21], v[104:105], v[24:25]
	v_pk_fma_f32 v[102:103], v[18:19], v[102:103], v[22:23]
	s_and_b64 vcc, exec, s[28:29]
	s_cbranch_vccz .LBB0_2429
; __device__ __forceinline__ unsigned cvt_pk_bf16(float lo, float hi) { unsigned r; asm("v_cvt_pk_bf16_f32 %0, %1, %2" : "=v"(r) : "v"(lo), "v"(hi)); return r; }
; __device__ __forceinline__ void ada_ln_r(f32x4 (&v)[4], const f32x4 (&sc1)[4], const f32x4 (&sh)[4]) {
;     float mean, rstd; ln_stats(v, mean, rstd);
; #pragma unroll
;     for (int j = 0; j < 4; ++j) v[j] = (v[j] - mean) * rstd * sc1[j] + sh[j];
; }
; __device__ __forceinline__ void store_row8_bf16(bf16* p, int lane, const f32x4 (&v)[4]) {
; #pragma unroll
;     for (int j2 = 0; j2 < 2; ++j2) { const f32x4 a = v[2 * j2], b = v[2 * j2 + 1]; u32x4 o; o.x = cvt_pk_bf16(a.x, a.y); o.y = cvt_pk_bf16(a.z, a.w); o.z = cvt_pk_bf16(b.x, b.y); o.w = cvt_pk_bf16(b.z, b.w); *(u32x4*)(p + 512 * j2 + 8 * lane) = o; }
; }
; __device__ __forceinline__ void phase_row2(const Frame& F, int l) {
;     ...
;             if (l + 1 == DEPTH) store_row8(((float*)F.out) + (size_t)row * D, lane, x);
;             else {
;                 store_row8_bf16(XB + (size_t)row * D, lane, x);
;                 ada_ln_r(x, sc1, sh);
;                 store_row8_bf16(H + (size_t)row * D, lane, x);
;             }
	v_mov_b32_e32 v156, v91
	v_mov_b32_e32 v157, v92
	v_mov_b32_e32 v158, v90
	v_mov_b32_e32 v159, v93
	v_pk_add_f32 v[156:157], v[156:157], v[158:159]
	v_mov_b32_e32 v158, v95
	v_mov_b32_e32 v159, v96
	v_mov_b32_e32 v160, v94
	v_mov_b32_e32 v161, v97
	v_pk_add_f32 v[158:159], v[158:159], v[160:161]
	v_add_f32_e32 v156, v156, v157
	v_pk_add_f32 v[158:159], v[158:159], v[158:159] op_sel_hi:[0,1]
	v_add_f32_e32 v157, 0, v156
	v_add_f32_e32 v161, v98, v99
	v_add_f32_e32 v163, v100, v101
	v_mov_b32_e32 v160, v102
	v_mov_b32_e32 v162, v103
	v_mov_b32_e32 v158, v104
	v_mov_b32_e32 v156, v105
	v_pk_add_f32 v[160:161], v[160:161], v[162:163]
	v_pk_add_f32 v[156:157], v[158:159], v[156:157]
	v_mov_b32_e32 v162, v92
	v_pk_add_f32 v[156:157], v[160:161], v[156:157]
	v_mov_b32_e32 v160, v90
	v_add_f32_e32 v156, v156, v157
	ds_bpermute_b32 v157, v1, v156
	v_mov_b32_e32 v164, v94
	v_mov_b32_e32 v176, v104
	v_mov_b32_e32 v178, v102
	s_ashr_i32 s27, s26, 31
	s_waitcnt lgkmcnt(0)
	v_add_f32_e32 v156, v156, v157
	ds_bpermute_b32 v157, v107, v156
	s_lshl_b64 s[40:41], s[26:27], 11
	s_waitcnt lgkmcnt(0)
	v_add_f32_e32 v156, v156, v157
	ds_bpermute_b32 v157, v152, v156
	s_waitcnt lgkmcnt(0)
	v_add_f32_e32 v156, v156, v157
	ds_bpermute_b32 v157, v153, v156
	s_waitcnt lgkmcnt(0)
	v_add_f32_e32 v156, v156, v157
	ds_bpermute_b32 v157, v154, v156
	s_waitcnt lgkmcnt(0)
	v_add_f32_e32 v156, v156, v157
	ds_bpermute_b32 v157, v155, v156
	s_waitcnt lgkmcnt(0)
	v_add_f32_e32 v180, v156, v157
	v_fmamk_f32 v161, v180, 0xba800000, v91
	v_fmac_f32_e32 v160, 0xba800000, v180
	v_fmamk_f32 v163, v180, 0xba800000, v93
	v_fmac_f32_e32 v162, 0xba800000, v180
	v_pk_mul_f32 v[156:157], v[162:163], v[162:163]
	v_pk_mul_f32 v[158:159], v[160:161], v[160:161]
	v_fmamk_f32 v165, v180, 0xba800000, v95
	v_pk_mov_b32 v[166:167], v[158:159], v[156:157] op_sel:[1,0]
	v_mov_b32_e32 v159, v157
	v_pk_add_f32 v[156:157], v[166:167], v[158:159]
	v_mov_b32_e32 v166, v96
	v_fmac_f32_e32 v164, 0xba800000, v180
	v_fmamk_f32 v167, v180, 0xba800000, v97
	v_fmac_f32_e32 v166, 0xba800000, v180
	v_pk_mul_f32 v[158:159], v[166:167], v[166:167]
	v_pk_mul_f32 v[168:169], v[164:165], v[164:165]
	v_pk_add_f32 v[156:157], v[156:157], v[156:157] op_sel_hi:[0,1]
	v_pk_mov_b32 v[170:171], v[168:169], v[158:159] op_sel:[1,0]
	v_mov_b32_e32 v169, v159
	v_pk_add_f32 v[158:159], v[170:171], v[168:169]
	v_mov_b32_e32 v168, v98
	v_fmac_f32_e32 v168, 0xba800000, v180
	v_mov_b32_e32 v170, v100
	v_fmamk_f32 v169, v180, 0xba800000, v99
	v_fmac_f32_e32 v170, 0xba800000, v180
	v_mul_f32_e32 v156, v168, v168
	v_fmamk_f32 v171, v180, 0xba800000, v101
	v_pk_fma_f32 v[172:173], v[168:169], v[168:169], v[156:157] op_sel_hi:[1,1,0]
	v_mul_f32_e32 v156, v170, v170
	v_pk_add_f32 v[158:159], v[158:159], v[158:159] op_sel_hi:[0,1]
	v_pk_fma_f32 v[174:175], v[170:171], v[170:171], v[156:157] op_sel_hi:[1,1,0]
	v_fmamk_f32 v177, v180, 0xba800000, v105
	v_fmac_f32_e32 v176, 0xba800000, v180
	v_fmamk_f32 v179, v180, 0xba800000, v103
	v_fmac_f32_e32 v178, 0xba800000, v180
	v_mul_f32_e32 v172, v178, v178
	v_mul_f32_e32 v174, v179, v179
	v_mul_f32_e32 v156, v176, v176
	v_mul_f32_e32 v158, v177, v177
	v_pk_add_f32 v[172:173], v[172:173], v[174:175]
	v_pk_add_f32 v[156:157], v[156:157], v[158:159]
	v_cvt_pk_bf16_f32 v158, v94, v95
	v_cvt_pk_bf16_f32 v159, v96, v97
	s_nop 0
	v_pk_add_f32 v[156:157], v[172:173], v[156:157]
	v_lshl_add_u64 v[172:173], v[108:109], 0, s[40:41]
	v_add_f32_e32 v156, v156, v157
	ds_bpermute_b32 v157, v1, v156
	s_waitcnt lgkmcnt(0)
	v_add_f32_e32 v156, v156, v157
	ds_bpermute_b32 v157, v107, v156
	s_waitcnt lgkmcnt(0)
	v_add_f32_e32 v156, v156, v157
	ds_bpermute_b32 v157, v152, v156
	s_waitcnt lgkmcnt(0)
	v_add_f32_e32 v156, v156, v157
	ds_bpermute_b32 v157, v153, v156
	s_waitcnt lgkmcnt(0)
	v_add_f32_e32 v156, v156, v157
	ds_bpermute_b32 v157, v154, v156
	s_waitcnt lgkmcnt(0)
	v_add_f32_e32 v174, v156, v157
	ds_bpermute_b32 v175, v155, v174
	v_cvt_pk_bf16_f32 v156, v90, v91
	v_cvt_pk_bf16_f32 v157, v92, v93
	global_store_dwordx4 v[172:173], v[156:159], off nt
	s_waitcnt lgkmcnt(0)
	v_add_f32_e32 v174, v174, v175
	v_fmamk_f32 v174, v174, 0x3a800000, v226
	v_mul_f32_e32 v175, 0x4f800000, v174
	v_cmp_gt_f32_e32 vcc, s2, v174
	v_cvt_pk_bf16_f32 v156, v98, v99
	v_cvt_pk_bf16_f32 v157, v100, v101
	s_nop 1
	v_cndmask_b32_e32 v174, v174, v175, vcc
	v_sqrt_f32_e32 v175, v174
	s_nop 0
	v_add_u32_e32 v158, -1, v175
	v_fma_f32 v159, -v158, v175, v174
	v_cmp_ge_f32_e64 s[0:1], 0, v159
	v_add_u32_e32 v159, 1, v175
	s_nop 0
	v_cndmask_b32_e64 v158, v175, v158, s[0:1]
	v_fma_f32 v175, -v159, v175, v174
	v_cmp_lt_f32_e64 s[0:1], 0, v175
	s_nop 1
	v_cndmask_b32_e64 v158, v158, v159, s[0:1]
	v_mul_f32_e32 v159, 0x37800000, v158
	v_cndmask_b32_e32 v158, v158, v159, vcc
	v_cmp_class_f32_e32 vcc, v174, v227
	v_cvt_pk_bf16_f32 v159, v104, v105
	s_nop 1
	v_cndmask_b32_e32 v174, v158, v174, vcc
	v_div_scale_f32 v175, s[0:1], v174, v174, 1.0
	v_rcp_f32_e32 v180, v175
	v_cvt_pk_bf16_f32 v158, v102, v103
	global_store_dwordx4 v[172:173], v[156:159], off offset:1024 nt
	s_nop 1
	v_fma_f32 v156, -v175, v180, 1.0
	v_fmac_f32_e32 v180, v156, v180
	v_div_scale_f32 v156, vcc, 1.0, v174, 1.0
	v_mul_f32_e32 v157, v156, v180
	v_fma_f32 v158, -v175, v157, v156
	v_fmac_f32_e32 v157, v158, v180
	v_fma_f32 v156, -v175, v157, v156
	v_div_fmas_f32 v156, v156, v180, v157
	v_div_fixup_f32 v156, v156, v174, 1.0
	v_pk_mul_f32 v[158:159], v[160:161], v[156:157] op_sel_hi:[1,0]
	v_pk_mul_f32 v[160:161], v[162:163], v[156:157] op_sel_hi:[1,0]
	v_pk_fma_f32 v[158:159], v[128:129], v[158:159], v[14:15]
	v_pk_mul_f32 v[162:163], v[164:165], v[156:157] op_sel_hi:[1,0]
	v_pk_mul_f32 v[164:165], v[166:167], v[156:157] op_sel_hi:[1,0]
	v_pk_mul_f32 v[166:167], v[168:169], v[156:157] op_sel_hi:[1,0]
	v_pk_mul_f32 v[168:169], v[170:171], v[156:157] op_sel_hi:[1,0]
	v_pk_mul_f32 v[170:171], v[178:179], v[156:157] op_sel_hi:[1,0]
	v_pk_mul_f32 v[156:157], v[176:177], v[156:157] op_sel_hi:[1,0]
	v_pk_fma_f32 v[160:161], v[130:131], v[160:161], v[16:17]
	v_pk_fma_f32 v[164:165], v[134:135], v[164:165], v[12:13]
	v_pk_fma_f32 v[162:163], v[132:133], v[162:163], v[10:11]
	v_pk_fma_f32 v[172:173], v[122:123], v[156:157], v[4:5]
	v_lshl_add_u64 v[174:175], v[110:111], 0, s[40:41]
	v_cvt_pk_bf16_f32 v156, v158, v159
	v_cvt_pk_bf16_f32 v157, v160, v161
	v_cvt_pk_bf16_f32 v158, v162, v163
	v_cvt_pk_bf16_f32 v159, v164, v165
	v_pk_fma_f32 v[168:169], v[126:127], v[168:169], v[8:9]
	v_pk_fma_f32 v[166:167], v[124:125], v[166:167], v[6:7]
	v_pk_fma_f32 v[170:171], v[120:121], v[170:171], v[2:3]
	global_store_dwordx4 v[174:175], v[156:159], off
	s_nop 1
	v_cvt_pk_bf16_f32 v156, v166, v167
	v_cvt_pk_bf16_f32 v157, v168, v169
	v_cvt_pk_bf16_f32 v158, v170, v171
	v_cvt_pk_bf16_f32 v159, v172, v173
	global_store_dwordx4 v[174:175], v[156:159], off offset:1024
	s_cbranch_execnz .LBB0_2426
	s_branch .LBB0_2430

; __device__ __forceinline__ f32x4 bf4lo(u32x4 q) { return (f32x4){__uint_as_float(q.x << 16), __uint_as_float(q.x & 0xffff0000u), __uint_as_float(q.y << 16), __uint_as_float(q.y & 0xffff0000u)}; }
; __device__ __forceinline__ f32x4 bf4hi(u32x4 q) { return (f32x4){__uint_as_float(q.z << 16), __uint_as_float(q.z & 0xffff0000u), __uint_as_float(q.w << 16), __uint_as_float(q.w & 0xffff0000u)}; }
; __device__ __forceinline__ void store_row8(float* p, int lane, const f32x4 (&v)[4]) {
; #pragma unroll
;     for (int q = 0; q < 4; ++q) *(f32x4*)(p + 512 * (q >> 1) + 8 * lane + 4 * (q & 1)) = v[q];
; }
; __device__ __forceinline__ void phase_row2(const Frame& F, int l) {
;     ...
;         for (int i = 0; i < 8; ++i) {
;             const int row = row0 + i;
;             if (i + 1 < 8) { const bf16* yk = (const bf16*)(F.ws + WS_YK) + (size_t)(row + 1) * 4 * D + 8 * lane;
; #pragma unroll
;                 for (int j2 = 0; j2 < 2; ++j2) { nxb[j2] = *(const u32x4*)(XB + (size_t)(row + 1) * D + 512 * j2 + 8 * lane);
; #pragma unroll
;                     for (int k = 0; k < 4; ++k) ny[k][j2] = *(const u32x4*)(yk + k * D + 512 * j2); } }
;             f32x4 x[4], y[4];
; #pragma unroll
;             for (int j2 = 0; j2 < 2; ++j2) { x[2 * j2] = bf4lo(cxb[j2]); x[2 * j2 + 1] = bf4hi(cxb[j2]);
;                 y[2 * j2] = (bf4lo(cy[0][j2]) + bf4lo(cy[1][j2])) + (bf4lo(cy[2][j2]) + bf4lo(cy[3][j2]));
;                 y[2 * j2 + 1] = (bf4hi(cy[0][j2]) + bf4hi(cy[1][j2])) + (bf4hi(cy[2][j2]) + bf4hi(cy[3][j2])); }
;             deepnorm_r(x, y, g1, lg, lb);
;             if (l + 1 == DEPTH) store_row8(((float*)F.out) + (size_t)row * D, lane, x);
.LBB0_2430:
	s_ashr_i32 s27, s26, 31
	s_lshl_b64 s[0:1], s[26:27], 12
	v_lshl_add_u64 v[156:157], v[114:115], 0, s[0:1]
	global_store_dwordx4 v[156:157], v[90:93], off nt
	global_store_dwordx4 v[156:157], v[94:97], off offset:16 nt
	global_store_dwordx4 v[156:157], v[98:101], off offset:2048 nt
	global_store_dwordx4 v[156:157], v[102:105], off offset:2064 nt
	s_branch .LBB0_2426
.LBB0_2431:
	s_waitcnt vmcnt(7)
	v_lshlrev_b32_e32 v94, 16, v82
	v_and_b32_e32 v95, 0xffff0000, v82
	v_lshlrev_b32_e32 v82, 16, v83
	v_and_b32_e32 v83, 0xffff0000, v83
	s_waitcnt vmcnt(5)
	v_lshlrev_b32_e32 v96, 16, v78
	v_and_b32_e32 v97, 0xffff0000, v78
	v_lshlrev_b32_e32 v78, 16, v79
	v_and_b32_e32 v79, 0xffff0000, v79
	v_pk_add_f32 v[94:95], v[94:95], v[96:97]
	v_pk_add_f32 v[78:79], v[82:83], v[78:79]
	s_waitcnt vmcnt(3)
	v_lshlrev_b32_e32 v82, 16, v74
	v_and_b32_e32 v83, 0xffff0000, v74
	v_lshlrev_b32_e32 v74, 16, v75
	v_and_b32_e32 v75, 0xffff0000, v75
	s_waitcnt vmcnt(1)
	v_lshlrev_b32_e32 v96, 16, v70
	v_and_b32_e32 v97, 0xffff0000, v70
	v_lshlrev_b32_e32 v70, 16, v71
	v_and_b32_e32 v71, 0xffff0000, v71
	v_pk_add_f32 v[82:83], v[82:83], v[96:97]
	v_pk_add_f32 v[70:71], v[74:75], v[70:71]
	v_pk_add_f32 v[74:75], v[94:95], v[82:83]
	v_pk_add_f32 v[70:71], v[78:79], v[70:71]
	v_lshlrev_b32_e32 v78, 16, v84
	v_and_b32_e32 v79, 0xffff0000, v84
	v_lshlrev_b32_e32 v82, 16, v85
	v_and_b32_e32 v83, 0xffff0000, v85
	v_lshlrev_b32_e32 v84, 16, v80
	v_and_b32_e32 v85, 0xffff0000, v80
	v_lshlrev_b32_e32 v80, 16, v81
	v_and_b32_e32 v81, 0xffff0000, v81
	v_pk_add_f32 v[78:79], v[78:79], v[84:85]
	v_pk_add_f32 v[80:81], v[82:83], v[80:81]
	v_lshlrev_b32_e32 v82, 16, v76
	v_and_b32_e32 v83, 0xffff0000, v76
	v_lshlrev_b32_e32 v84, 16, v72
	v_and_b32_e32 v85, 0xffff0000, v72
	v_lshlrev_b32_e32 v76, 16, v77
	v_and_b32_e32 v77, 0xffff0000, v77
	v_lshlrev_b32_e32 v72, 16, v73
	v_and_b32_e32 v73, 0xffff0000, v73
	v_pk_add_f32 v[82:83], v[82:83], v[84:85]
	v_pk_add_f32 v[72:73], v[76:77], v[72:73]
	v_pk_add_f32 v[76:77], v[78:79], v[82:83]
	v_lshlrev_b32_e32 v82, 16, v62
	v_and_b32_e32 v83, 0xffff0000, v62
	v_lshlrev_b32_e32 v62, 16, v63
	v_and_b32_e32 v63, 0xffff0000, v63
	v_lshlrev_b32_e32 v84, 16, v58
	v_and_b32_e32 v85, 0xffff0000, v58
	v_lshlrev_b32_e32 v58, 16, v59
	v_and_b32_e32 v59, 0xffff0000, v59
	v_pk_add_f32 v[82:83], v[82:83], v[84:85]
	v_pk_add_f32 v[58:59], v[62:63], v[58:59]
	v_lshlrev_b32_e32 v62, 16, v54
	v_and_b32_e32 v63, 0xffff0000, v54
	v_lshlrev_b32_e32 v54, 16, v55
	v_and_b32_e32 v55, 0xffff0000, v55
	s_waitcnt vmcnt(0)
	v_lshlrev_b32_e32 v84, 16, v50
	v_and_b32_e32 v85, 0xffff0000, v50
	v_lshlrev_b32_e32 v50, 16, v51
	v_and_b32_e32 v51, 0xffff0000, v51
	v_pk_add_f32 v[62:63], v[62:63], v[84:85]
	v_pk_add_f32 v[50:51], v[54:55], v[50:51]
	v_pk_add_f32 v[54:55], v[82:83], v[62:63]
	v_pk_add_f32 v[50:51], v[58:59], v[50:51]
	v_lshlrev_b32_e32 v58, 16, v64
	v_and_b32_e32 v59, 0xffff0000, v64
	v_lshlrev_b32_e32 v62, 16, v65
	v_and_b32_e32 v63, 0xffff0000, v65
	v_lshlrev_b32_e32 v64, 16, v60
	v_and_b32_e32 v65, 0xffff0000, v60
	v_lshlrev_b32_e32 v60, 16, v61
	v_and_b32_e32 v61, 0xffff0000, v61
	v_pk_add_f32 v[58:59], v[58:59], v[64:65]
	v_pk_add_f32 v[60:61], v[62:63], v[60:61]
	v_lshlrev_b32_e32 v62, 16, v56
	v_and_b32_e32 v63, 0xffff0000, v56
	v_lshlrev_b32_e32 v56, 16, v57
	v_and_b32_e32 v57, 0xffff0000, v57
	v_lshlrev_b32_e32 v64, 16, v52
	v_and_b32_e32 v65, 0xffff0000, v52
	v_lshlrev_b32_e32 v52, 16, v53
	v_and_b32_e32 v53, 0xffff0000, v53
	v_pk_add_f32 v[62:63], v[62:63], v[64:65]
	v_pk_add_f32 v[52:53], v[56:57], v[52:53]
	v_lshlrev_b32_e32 v90, 16, v86
	v_and_b32_e32 v91, 0xffff0000, v86
	v_lshlrev_b32_e32 v86, 16, v87
	v_and_b32_e32 v87, 0xffff0000, v87
	v_pk_add_f32 v[72:73], v[80:81], v[72:73]
	v_pk_add_f32 v[52:53], v[60:61], v[52:53]
	v_pk_add_f32 v[56:57], v[58:59], v[62:63]
	v_pk_mul_f32 v[58:59], v[150:151], v[74:75]
	v_pk_mul_f32 v[60:61], v[148:149], v[70:71]
	v_lshlrev_b32_e32 v92, 16, v88
	v_and_b32_e32 v93, 0xffff0000, v88
	v_lshlrev_b32_e32 v88, 16, v89
	v_and_b32_e32 v89, 0xffff0000, v89
	v_lshlrev_b32_e32 v78, 16, v66
	v_and_b32_e32 v79, 0xffff0000, v66
	v_lshlrev_b32_e32 v66, 16, v67
	v_and_b32_e32 v67, 0xffff0000, v67
	v_lshlrev_b32_e32 v80, 16, v68
	v_and_b32_e32 v81, 0xffff0000, v68
	v_lshlrev_b32_e32 v68, 16, v69
	v_and_b32_e32 v69, 0xffff0000, v69
	v_pk_fma_f32 v[60:61], v[86:87], s[16:17], v[60:61] op_sel_hi:[1,0,1]
	v_pk_fma_f32 v[58:59], v[90:91], s[16:17], v[58:59] op_sel_hi:[1,0,1]
	v_pk_mul_f32 v[62:63], v[146:147], v[76:77]
	v_pk_mul_f32 v[64:65], v[144:145], v[72:73]
	v_pk_mul_f32 v[50:51], v[140:141], v[50:51]
	v_pk_mul_f32 v[52:53], v[136:137], v[52:53]
	v_pk_fma_f32 v[64:65], v[88:89], s[16:17], v[64:65] op_sel_hi:[1,0,1]
	v_pk_fma_f32 v[62:63], v[92:93], s[16:17], v[62:63] op_sel_hi:[1,0,1]
	v_pk_fma_f32 v[50:51], v[66:67], s[16:17], v[50:51] op_sel_hi:[1,0,1]
	v_pk_fma_f32 v[52:53], v[68:69], s[16:17], v[52:53] op_sel_hi:[1,0,1]
	v_pk_mov_b32 v[66:67], v[58:59], v[60:61] op_sel:[1,0]
	v_mov_b32_e32 v68, v58
	v_mov_b32_e32 v69, v61
	v_pk_add_f32 v[66:67], v[66:67], v[68:69]
	v_pk_mov_b32 v[68:69], v[62:63], v[64:65] op_sel:[1,0]
	v_mov_b32_e32 v70, v62
	v_mov_b32_e32 v71, v65
	v_pk_mul_f32 v[54:55], v[142:143], v[54:55]
	v_pk_mul_f32 v[56:57], v[138:139], v[56:57]
	v_pk_add_f32 v[68:69], v[68:69], v[70:71]
	v_pk_fma_f32 v[54:55], v[78:79], s[16:17], v[54:55] op_sel_hi:[1,0,1]
	v_pk_fma_f32 v[56:57], v[80:81], s[16:17], v[56:57] op_sel_hi:[1,0,1]
	v_add_f32_e32 v66, v66, v67
	v_pk_add_f32 v[68:69], v[68:69], v[68:69] op_sel_hi:[0,1]
	v_add_f32_e32 v67, 0, v66
	v_add_f32_e32 v71, v54, v55
	v_add_f32_e32 v73, v50, v51
	v_mov_b32_e32 v68, v56
	v_mov_b32_e32 v66, v57
	v_mov_b32_e32 v70, v52
	v_mov_b32_e32 v72, v53
	v_pk_add_f32 v[66:67], v[68:69], v[66:67]
	v_pk_add_f32 v[68:69], v[70:71], v[72:73]
	s_or_b32 s26, s36, 7
	v_pk_add_f32 v[66:67], v[66:67], v[68:69]
	s_nop 0
	v_add_f32_e32 v66, v66, v67
	ds_bpermute_b32 v67, v1, v66
	s_waitcnt lgkmcnt(0)
; __device__ __forceinline__ void deepnorm_r(f32x4 (&x)[4], const f32x4 (&y)[4], const f32x4 (&g1)[4], const f32x4 (&lg)[4], const f32x4 (&lb)[4]) {
; #pragma unroll
;     for (int j = 0; j < 4; ++j) x[j] = ALPHA * x[j] + g1[j] * y[j];
;     float mean, rstd; ln_stats(x, mean, rstd);
; #pragma unroll
;     for (int j = 0; j < 4; ++j) x[j] = (x[j] - mean) * rstd * lg[j] + lb[j];
; }
	v_add_f32_e32 v66, v66, v67
	ds_bpermute_b32 v67, v107, v66
	s_waitcnt lgkmcnt(0)
	v_add_f32_e32 v66, v66, v67
	ds_bpermute_b32 v67, v152, v66
	s_waitcnt lgkmcnt(0)
	v_add_f32_e32 v66, v66, v67
	ds_bpermute_b32 v67, v153, v66
	s_waitcnt lgkmcnt(0)
	v_add_f32_e32 v66, v66, v67
	ds_bpermute_b32 v67, v154, v66
	s_waitcnt lgkmcnt(0)
	v_add_f32_e32 v66, v66, v67
	ds_bpermute_b32 v67, v155, v66
	s_waitcnt lgkmcnt(0)
	v_add_f32_e32 v74, v66, v67
	v_fmamk_f32 v59, v74, 0xba800000, v59
	v_fmac_f32_e32 v58, 0xba800000, v74
	v_fmamk_f32 v61, v74, 0xba800000, v61
	v_fmac_f32_e32 v60, 0xba800000, v74
	v_pk_mul_f32 v[66:67], v[60:61], v[60:61]
	v_pk_mul_f32 v[68:69], v[58:59], v[58:59]
	v_fmamk_f32 v63, v74, 0xba800000, v63
	v_pk_mov_b32 v[70:71], v[68:69], v[66:67] op_sel:[1,0]
	v_mov_b32_e32 v69, v67
	v_pk_add_f32 v[66:67], v[70:71], v[68:69]
	v_fmac_f32_e32 v62, 0xba800000, v74
	v_fmamk_f32 v65, v74, 0xba800000, v65
	v_fmac_f32_e32 v64, 0xba800000, v74
	v_pk_add_f32 v[66:67], v[66:67], v[66:67] op_sel_hi:[0,1]
	v_pk_mul_f32 v[68:69], v[64:65], v[64:65]
	v_pk_mul_f32 v[70:71], v[62:63], v[62:63]
	v_fmac_f32_e32 v54, 0xba800000, v74
	v_pk_mov_b32 v[72:73], v[70:71], v[68:69] op_sel:[1,0]
	v_mov_b32_e32 v71, v69
	v_fmamk_f32 v55, v74, 0xba800000, v55
	v_fmac_f32_e32 v50, 0xba800000, v74
	v_mul_f32_e32 v66, v54, v54
	v_pk_add_f32 v[68:69], v[72:73], v[70:71]
	v_fmamk_f32 v51, v74, 0xba800000, v51
	v_pk_fma_f32 v[70:71], v[54:55], v[54:55], v[66:67] op_sel_hi:[1,1,0]
	v_mul_f32_e32 v66, v50, v50
	v_pk_add_f32 v[68:69], v[68:69], v[68:69] op_sel_hi:[0,1]
	v_pk_fma_f32 v[72:73], v[50:51], v[50:51], v[66:67] op_sel_hi:[1,1,0]
	v_fmamk_f32 v53, v74, 0xba800000, v53
	v_fmac_f32_e32 v52, 0xba800000, v74
	v_fmamk_f32 v57, v74, 0xba800000, v57
	v_fmac_f32_e32 v56, 0xba800000, v74
	v_mul_f32_e32 v70, v56, v56
	v_mul_f32_e32 v72, v57, v57
	v_mul_f32_e32 v66, v52, v52
	v_mul_f32_e32 v68, v53, v53
	v_pk_add_f32 v[70:71], v[70:71], v[72:73]
	v_pk_add_f32 v[66:67], v[66:67], v[68:69]
	s_nop 0
	v_pk_add_f32 v[66:67], v[70:71], v[66:67]
	s_nop 0
	v_add_f32_e32 v66, v66, v67
	ds_bpermute_b32 v67, v1, v66
	s_waitcnt lgkmcnt(0)
	v_add_f32_e32 v66, v66, v67
	ds_bpermute_b32 v67, v107, v66
	s_waitcnt lgkmcnt(0)
	v_add_f32_e32 v66, v66, v67
	ds_bpermute_b32 v67, v152, v66
	s_waitcnt lgkmcnt(0)
	v_add_f32_e32 v66, v66, v67
	ds_bpermute_b32 v67, v153, v66
	s_waitcnt lgkmcnt(0)
	v_add_f32_e32 v66, v66, v67
	ds_bpermute_b32 v67, v154, v66
	s_waitcnt lgkmcnt(0)
	v_add_f32_e32 v66, v66, v67
	ds_bpermute_b32 v67, v155, v66
	s_waitcnt lgkmcnt(0)
	v_add_f32_e32 v66, v66, v67
	v_fmamk_f32 v66, v66, 0x3a800000, v226
	v_mul_f32_e32 v67, 0x4f800000, v66
	v_cmp_gt_f32_e32 vcc, s2, v66
	s_nop 1
	v_cndmask_b32_e32 v66, v66, v67, vcc
	v_sqrt_f32_e32 v67, v66
	s_nop 0
	v_add_u32_e32 v68, -1, v67
	v_fma_f32 v69, -v68, v67, v66
	v_cmp_ge_f32_e64 s[0:1], 0, v69
	v_add_u32_e32 v69, 1, v67
	s_nop 0
	v_cndmask_b32_e64 v68, v67, v68, s[0:1]
	v_fma_f32 v67, -v69, v67, v66
	v_cmp_lt_f32_e64 s[0:1], 0, v67
	s_nop 1
	v_cndmask_b32_e64 v67, v68, v69, s[0:1]
	v_mul_f32_e32 v68, 0x37800000, v67
	v_cndmask_b32_e32 v67, v67, v68, vcc
	v_cmp_class_f32_e32 vcc, v66, v227
	s_nop 1
	v_cndmask_b32_e32 v66, v67, v66, vcc
	v_div_scale_f32 v67, s[0:1], v66, v66, 1.0
	v_rcp_f32_e32 v68, v67
	s_mov_b64 s[0:1], -1
	v_fma_f32 v69, -v67, v68, 1.0
	v_fmac_f32_e32 v68, v69, v68
	v_div_scale_f32 v69, vcc, 1.0, v66, 1.0
	v_mul_f32_e32 v70, v69, v68
	v_fma_f32 v71, -v67, v70, v69
	v_fmac_f32_e32 v70, v71, v68
	v_fma_f32 v67, -v67, v70, v69
	v_div_fmas_f32 v67, v67, v68, v70
	v_div_fixup_f32 v66, v67, v66, 1.0
	v_pk_mul_f32 v[58:59], v[58:59], v[66:67] op_sel_hi:[1,0]
	v_pk_mul_f32 v[60:61], v[60:61], v[66:67] op_sel_hi:[1,0]
	v_pk_fma_f32 v[42:43], v[42:43], v[58:59], v[46:47]
	v_pk_fma_f32 v[44:45], v[44:45], v[60:61], v[48:49]
	v_pk_mul_f32 v[46:47], v[62:63], v[66:67] op_sel_hi:[1,0]
	v_pk_mul_f32 v[48:49], v[64:65], v[66:67] op_sel_hi:[1,0]
	v_pk_fma_f32 v[34:35], v[34:35], v[46:47], v[38:39]
	v_pk_fma_f32 v[36:37], v[36:37], v[48:49], v[40:41]
	v_pk_mul_f32 v[38:39], v[54:55], v[66:67] op_sel_hi:[1,0]
	v_pk_mul_f32 v[40:41], v[50:51], v[66:67] op_sel_hi:[1,0]
	v_pk_fma_f32 v[26:27], v[26:27], v[38:39], v[30:31]
	v_pk_fma_f32 v[28:29], v[28:29], v[40:41], v[32:33]
	v_pk_mul_f32 v[30:31], v[56:57], v[66:67] op_sel_hi:[1,0]
	v_pk_mul_f32 v[32:33], v[52:53], v[66:67] op_sel_hi:[1,0]
	v_pk_fma_f32 v[18:19], v[18:19], v[30:31], v[22:23]
	v_pk_fma_f32 v[20:21], v[20:21], v[32:33], v[24:25]
	s_andn2_b64 vcc, exec, s[28:29]
	s_cbranch_vccnz .LBB0_2433
; __device__ __forceinline__ unsigned cvt_pk_bf16(float lo, float hi) { unsigned r; asm("v_cvt_pk_bf16_f32 %0, %1, %2" : "=v"(r) : "v"(lo), "v"(hi)); return r; }
; __device__ __forceinline__ void store_row8(float* p, int lane, const f32x4 (&v)[4]) {
; #pragma unroll
;     for (int q = 0; q < 4; ++q) *(f32x4*)(p + 512 * (q >> 1) + 8 * lane + 4 * (q & 1)) = v[q];
; }
; __device__ __forceinline__ void store_row8_bf16(bf16* p, int lane, const f32x4 (&v)[4]) {
; #pragma unroll
;     for (int j2 = 0; j2 < 2; ++j2) { const f32x4 a = v[2 * j2], b = v[2 * j2 + 1]; u32x4 o; o.x = cvt_pk_bf16(a.x, a.y); o.y = cvt_pk_bf16(a.z, a.w); o.z = cvt_pk_bf16(b.x, b.y); o.w = cvt_pk_bf16(b.z, b.w); *(u32x4*)(p + 512 * j2 + 8 * lane) = o; }
; }
; __device__ __forceinline__ void phase_row2(const Frame& F, int l) {
;     ...
;             if (l + 1 == DEPTH) store_row8(((float*)F.out) + (size_t)row * D, lane, x);
;             else {
;                 store_row8_bf16(XB + (size_t)row * D, lane, x);
;                 ada_ln_r(x, sc1, sh);
;                 store_row8_bf16(H + (size_t)row * D, lane, x);
;             }
	v_mov_b32_e32 v22, v43
	v_mov_b32_e32 v23, v44
	v_mov_b32_e32 v24, v42
	v_mov_b32_e32 v25, v45
	v_pk_add_f32 v[22:23], v[22:23], v[24:25]
	v_mov_b32_e32 v24, v35
	v_mov_b32_e32 v25, v36
	v_mov_b32_e32 v30, v34
	v_mov_b32_e32 v31, v37
	v_pk_add_f32 v[24:25], v[24:25], v[30:31]
	v_add_f32_e32 v22, v22, v23
	v_pk_add_f32 v[24:25], v[24:25], v[24:25] op_sel_hi:[0,1]
	v_add_f32_e32 v23, 0, v22
	v_add_f32_e32 v31, v26, v27
	v_add_f32_e32 v33, v28, v29
	v_mov_b32_e32 v30, v18
	v_mov_b32_e32 v32, v19
	v_mov_b32_e32 v24, v20
	v_mov_b32_e32 v22, v21
	v_pk_add_f32 v[30:31], v[30:31], v[32:33]
	v_pk_add_f32 v[22:23], v[24:25], v[22:23]
	v_mov_b32_e32 v32, v44
	v_pk_add_f32 v[22:23], v[30:31], v[22:23]
	v_mov_b32_e32 v30, v42
	v_add_f32_e32 v22, v22, v23
	ds_bpermute_b32 v23, v1, v22
	v_mov_b32_e32 v38, v34
	v_mov_b32_e32 v54, v20
	v_mov_b32_e32 v56, v18
	s_ashr_i32 s27, s26, 31
	s_waitcnt lgkmcnt(0)
	v_add_f32_e32 v22, v22, v23
	ds_bpermute_b32 v23, v107, v22
	s_lshl_b64 s[36:37], s[26:27], 11
	s_waitcnt lgkmcnt(0)
	v_add_f32_e32 v22, v22, v23
	ds_bpermute_b32 v23, v152, v22
	s_waitcnt lgkmcnt(0)
	v_add_f32_e32 v22, v22, v23
	ds_bpermute_b32 v23, v153, v22
	s_waitcnt lgkmcnt(0)
	v_add_f32_e32 v22, v22, v23
	ds_bpermute_b32 v23, v154, v22
	s_waitcnt lgkmcnt(0)
	v_add_f32_e32 v22, v22, v23
	ds_bpermute_b32 v23, v155, v22
	s_waitcnt lgkmcnt(0)
	v_add_f32_e32 v58, v22, v23
	v_fmamk_f32 v31, v58, 0xba800000, v43
	v_fmac_f32_e32 v30, 0xba800000, v58
	v_fmamk_f32 v33, v58, 0xba800000, v45
	v_fmac_f32_e32 v32, 0xba800000, v58
	v_pk_mul_f32 v[22:23], v[32:33], v[32:33]
	v_pk_mul_f32 v[24:25], v[30:31], v[30:31]
	v_fmamk_f32 v39, v58, 0xba800000, v35
	v_pk_mov_b32 v[40:41], v[24:25], v[22:23] op_sel:[1,0]
	v_mov_b32_e32 v25, v23
	v_pk_add_f32 v[22:23], v[40:41], v[24:25]
	v_mov_b32_e32 v40, v36
	v_fmac_f32_e32 v38, 0xba800000, v58
	v_fmamk_f32 v41, v58, 0xba800000, v37
	v_fmac_f32_e32 v40, 0xba800000, v58
	v_pk_mul_f32 v[24:25], v[40:41], v[40:41]
	v_pk_mul_f32 v[46:47], v[38:39], v[38:39]
	v_pk_add_f32 v[22:23], v[22:23], v[22:23] op_sel_hi:[0,1]
	v_pk_mov_b32 v[48:49], v[46:47], v[24:25] op_sel:[1,0]
	v_mov_b32_e32 v47, v25
	v_pk_add_f32 v[24:25], v[48:49], v[46:47]
	v_mov_b32_e32 v46, v26
	v_fmac_f32_e32 v46, 0xba800000, v58
	v_mov_b32_e32 v48, v28
	v_fmamk_f32 v47, v58, 0xba800000, v27
	v_fmac_f32_e32 v48, 0xba800000, v58
	v_mul_f32_e32 v22, v46, v46
	v_fmamk_f32 v49, v58, 0xba800000, v29
	v_pk_fma_f32 v[50:51], v[46:47], v[46:47], v[22:23] op_sel_hi:[1,1,0]
	v_mul_f32_e32 v22, v48, v48
	v_pk_add_f32 v[24:25], v[24:25], v[24:25] op_sel_hi:[0,1]
	v_pk_fma_f32 v[52:53], v[48:49], v[48:49], v[22:23] op_sel_hi:[1,1,0]
	v_fmamk_f32 v55, v58, 0xba800000, v21
	v_fmac_f32_e32 v54, 0xba800000, v58
	v_fmamk_f32 v57, v58, 0xba800000, v19
	v_fmac_f32_e32 v56, 0xba800000, v58
	v_mul_f32_e32 v50, v56, v56
	v_mul_f32_e32 v52, v57, v57
	v_mul_f32_e32 v22, v54, v54
	v_mul_f32_e32 v24, v55, v55
	v_pk_add_f32 v[50:51], v[50:51], v[52:53]
	v_pk_add_f32 v[22:23], v[22:23], v[24:25]
	v_cvt_pk_bf16_f32 v24, v34, v35
	v_cvt_pk_bf16_f32 v25, v36, v37
	s_nop 0
	v_pk_add_f32 v[22:23], v[50:51], v[22:23]
	v_lshl_add_u64 v[50:51], v[108:109], 0, s[36:37]
	v_add_f32_e32 v22, v22, v23
	ds_bpermute_b32 v23, v1, v22
	s_waitcnt lgkmcnt(0)
	v_add_f32_e32 v22, v22, v23
	ds_bpermute_b32 v23, v107, v22
	s_waitcnt lgkmcnt(0)
	v_add_f32_e32 v22, v22, v23
	ds_bpermute_b32 v23, v152, v22
	s_waitcnt lgkmcnt(0)
	v_add_f32_e32 v22, v22, v23
	ds_bpermute_b32 v23, v153, v22
	s_waitcnt lgkmcnt(0)
	v_add_f32_e32 v22, v22, v23
	ds_bpermute_b32 v23, v154, v22
	s_waitcnt lgkmcnt(0)
	v_add_f32_e32 v52, v22, v23
	ds_bpermute_b32 v53, v155, v52
	v_cvt_pk_bf16_f32 v22, v42, v43
	v_cvt_pk_bf16_f32 v23, v44, v45
	global_store_dwordx4 v[50:51], v[22:25], off nt
	s_waitcnt lgkmcnt(0)
	v_add_f32_e32 v52, v52, v53
	v_fmamk_f32 v52, v52, 0x3a800000, v226
	v_mul_f32_e32 v53, 0x4f800000, v52
	v_cmp_gt_f32_e32 vcc, s2, v52
	v_cvt_pk_bf16_f32 v22, v26, v27
	v_cvt_pk_bf16_f32 v23, v28, v29
	s_nop 1
	v_cndmask_b32_e32 v52, v52, v53, vcc
	v_sqrt_f32_e32 v53, v52
	s_nop 0
	v_add_u32_e32 v24, -1, v53
	v_fma_f32 v25, -v24, v53, v52
	v_cmp_ge_f32_e64 s[0:1], 0, v25
	v_add_u32_e32 v25, 1, v53
	s_nop 0
	v_cndmask_b32_e64 v24, v53, v24, s[0:1]
	v_fma_f32 v53, -v25, v53, v52
	v_cmp_lt_f32_e64 s[0:1], 0, v53
	s_nop 1
	v_cndmask_b32_e64 v24, v24, v25, s[0:1]
	v_mul_f32_e32 v25, 0x37800000, v24
	v_cndmask_b32_e32 v24, v24, v25, vcc
	v_cmp_class_f32_e32 vcc, v52, v227
	v_cvt_pk_bf16_f32 v25, v20, v21
	s_nop 1
	v_cndmask_b32_e32 v52, v24, v52, vcc
	v_div_scale_f32 v53, s[0:1], v52, v52, 1.0
	v_rcp_f32_e32 v58, v53
	v_cvt_pk_bf16_f32 v24, v18, v19
	global_store_dwordx4 v[50:51], v[22:25], off offset:1024 nt
	s_mov_b64 s[0:1], 0
	s_nop 0
	v_fma_f32 v22, -v53, v58, 1.0
	v_fmac_f32_e32 v58, v22, v58
	v_div_scale_f32 v22, vcc, 1.0, v52, 1.0
	v_mul_f32_e32 v23, v22, v58
	v_fma_f32 v24, -v53, v23, v22
	v_fmac_f32_e32 v23, v24, v58
	v_fma_f32 v22, -v53, v23, v22
	v_div_fmas_f32 v22, v22, v58, v23
	v_div_fixup_f32 v22, v22, v52, 1.0
	v_pk_mul_f32 v[24:25], v[30:31], v[22:23] op_sel_hi:[1,0]
	v_pk_mul_f32 v[30:31], v[32:33], v[22:23] op_sel_hi:[1,0]
	v_pk_fma_f32 v[14:15], v[128:129], v[24:25], v[14:15]
	v_pk_mul_f32 v[24:25], v[38:39], v[22:23] op_sel_hi:[1,0]
	v_pk_fma_f32 v[16:17], v[130:131], v[30:31], v[16:17]
	v_pk_mul_f32 v[30:31], v[40:41], v[22:23] op_sel_hi:[1,0]
	v_pk_fma_f32 v[10:11], v[132:133], v[24:25], v[10:11]
	v_pk_mul_f32 v[24:25], v[46:47], v[22:23] op_sel_hi:[1,0]
	v_pk_fma_f32 v[12:13], v[134:135], v[30:31], v[12:13]
	v_pk_mul_f32 v[30:31], v[48:49], v[22:23] op_sel_hi:[1,0]
	v_pk_fma_f32 v[6:7], v[124:125], v[24:25], v[6:7]
	v_pk_mul_f32 v[24:25], v[56:57], v[22:23] op_sel_hi:[1,0]
	v_pk_mul_f32 v[22:23], v[54:55], v[22:23] op_sel_hi:[1,0]
	v_pk_fma_f32 v[8:9], v[126:127], v[30:31], v[8:9]
	v_pk_fma_f32 v[22:23], v[122:123], v[22:23], v[4:5]
	v_pk_fma_f32 v[24:25], v[120:121], v[24:25], v[2:3]
	v_lshl_add_u64 v[30:31], v[110:111], 0, s[36:37]
	v_cvt_pk_bf16_f32 v2, v14, v15
	v_cvt_pk_bf16_f32 v3, v16, v17
	v_cvt_pk_bf16_f32 v4, v10, v11
	v_cvt_pk_bf16_f32 v5, v12, v13
	global_store_dwordx4 v[30:31], v[2:5], off
	s_nop 1
	v_cvt_pk_bf16_f32 v2, v6, v7
	v_cvt_pk_bf16_f32 v3, v8, v9
	v_cvt_pk_bf16_f32 v4, v24, v25
	v_cvt_pk_bf16_f32 v5, v22, v23
	global_store_dwordx4 v[30:31], v[2:5], off offset:1024
.LBB0_2433:
	s_andn2_b64 vcc, exec, s[0:1]
	s_cbranch_vccnz .LBB0_2422
	s_ashr_i32 s27, s26, 31
	s_lshl_b64 s[0:1], s[26:27], 12
	v_lshl_add_u64 v[2:3], v[114:115], 0, s[0:1]
	global_store_dwordx4 v[2:3], v[42:45], off nt
	global_store_dwordx4 v[2:3], v[34:37], off offset:16 nt
	global_store_dwordx4 v[2:3], v[26:29], off offset:2048 nt
	global_store_dwordx4 v[2:3], v[18:21], off offset:2064 nt
	s_branch .LBB0_2422
